# grid barrier: the per-CU L1 invalidate (acquire) is issued at arrival, overlapped with the arrival atomic / write-back / polling, instead of after the poll succeeds; on top of the P6 slot permutation
# speedup vs baseline: 1.0147x; 1.0107x over previous
; DI unsigned xb_ld(unsigned* p)              { return __hip_atomic_load(p, __ATOMIC_RELAXED, __HIP_MEMORY_SCOPE_AGENT); }
; DI unsigned xb_add(unsigned* p, unsigned v) { return __hip_atomic_fetch_add(p, v, __ATOMIC_RELAXED, __HIP_MEMORY_SCOPE_AGENT); }
; #define XB_SPIN(cond, bar) do { unsigned _sp = 0; while (cond) { __builtin_amdgcn_s_sleep(1); \
;     if ((++_sp & 255u) == 0u) { if (xb_ld(&(bar)[XB_TMO])) break; if (_sp > XB_SPIN_CAP) { atomicAdd(&(bar)[XB_TMO], 1u); break; } } } } while (0)
; DI void xcd_barrier(const XcdBarrier& b) {
;     asm volatile("s_waitcnt vmcnt(0)" ::: "memory");
;     __syncthreads();
;     if (threadIdx.x == 0) {
;         unsigned* bar = b.bar;
;         __builtin_amdgcn_s_waitcnt(0);
;         unsigned nloc = b.st[0], nx = b.st[1];
;         if (nloc == 0u) { xcd_barrier_complete(bar, b.x, nloc, nx); b.st[0] = nloc; b.st[1] = nx; }
;         const unsigned old = xb_add(&bar[XB_XSUB(b.x)], 1u);
;         const unsigned gen = old / nloc;
;         if (old + 1u == (gen + 1u) * nloc) {
;             __builtin_amdgcn_fence(__ATOMIC_RELEASE, "agent");
;             asm volatile("s_waitcnt vmcnt(0)" ::: "memory");
;             const unsigned og = xb_add(&bar[XB_TOP], 1u);
;             const unsigned tg = og / nx;
;             if (og + 1u == (tg + 1u) * nx) xb_add(&bar[XB_TOPGEN], 1u);
;             else XB_SPIN(xb_ld(&bar[XB_TOPGEN]) == tg, bar);
;             __builtin_amdgcn_fence(__ATOMIC_ACQUIRE, "agent");
;             xb_add(&bar[XB_XGEN(b.x)], 1u);
.LBB0_87:
	s_lshl_b32 s0, s96, 8
	v_mov_b32_e32 v0, s0
	v_add_u32_e32 v0, 0x1000, v0
	v_mov_b32_e32 v3, 1
	global_atomic_add v3, v0, v3, s[68:69] offset:1024 sc0
	buffer_inv sc1
	s_waitcnt lgkmcnt(0)
	v_cvt_f32_u32_e32 v0, v2
	v_sub_u32_e32 v4, 0, v2
	v_rcp_iflag_f32_e32 v0, v0
	s_nop 0
	v_mul_f32_e32 v0, 0x4f7ffffe, v0
	v_cvt_u32_f32_e32 v0, v0
	v_mul_lo_u32 v4, v4, v0
	v_mul_hi_u32 v4, v0, v4
	v_add_u32_e32 v0, v0, v4
	s_waitcnt vmcnt(1)
	v_mul_hi_u32 v0, v3, v0
	v_mul_lo_u32 v4, v0, v2
	v_sub_u32_e32 v4, v3, v4
	v_add_u32_e32 v5, 1, v0
	v_cmp_ge_u32_e32 vcc, v4, v2
	v_add_u32_e32 v3, 1, v3
	s_nop 0
	v_cndmask_b32_e32 v0, v0, v5, vcc
	v_sub_u32_e32 v5, v4, v2
	v_cndmask_b32_e32 v4, v4, v5, vcc
	v_add_u32_e32 v5, 1, v0
	v_cmp_ge_u32_e32 vcc, v4, v2
	s_nop 1
	v_cndmask_b32_e32 v0, v0, v5, vcc
	v_mul_lo_u32 v4, v2, v0
	v_add_u32_e32 v2, v4, v2
	v_cmp_ne_u32_e32 vcc, v3, v2
	v_add_u32_e32 v5, 1, v0
	v_mul_lo_u32 v5, v5, v1
	v_mov_b32_e32 v4, 0x3000
	s_cbranch_vccnz .Lxb0_pre
	buffer_wbl2 sc1
	s_waitcnt vmcnt(0) lgkmcnt(0)
	v_mov_b32_e32 v3, 1
	global_atomic_add v4, v3, s[68:69] offset:1024
	s_branch .Lxb0_poll
.Lxb0_pre:
.Lxb0_poll:
	s_mov_b32 s1, 0

; DI unsigned xb_ld(unsigned* p)              { return __hip_atomic_load(p, __ATOMIC_RELAXED, __HIP_MEMORY_SCOPE_AGENT); }
; #define XB_SPIN(cond, bar) do { unsigned _sp = 0; while (cond) { __builtin_amdgcn_s_sleep(1); \
;     if ((++_sp & 255u) == 0u) { if (xb_ld(&(bar)[XB_TMO])) break; if (_sp > XB_SPIN_CAP) { atomicAdd(&(bar)[XB_TMO], 1u); break; } } } } while (0)
; DI void xcd_barrier(const XcdBarrier& b) {
;     ...
;         } else {
;             XB_SPIN(xb_ld(&bar[XB_XGEN(b.x)]) == gen, bar);
;             __builtin_amdgcn_fence(__ATOMIC_ACQUIRE, "agent");
;             asm volatile("s_waitcnt vmcnt(0)" ::: "memory");
;         }
;     }
;     __syncthreads();
.Lxb0_done:
.LBB0_119:
	s_or_b64 exec, exec, s[6:7]
	s_waitcnt lgkmcnt(0)
	s_barrier

; DI unsigned xb_ld(unsigned* p)              { return __hip_atomic_load(p, __ATOMIC_RELAXED, __HIP_MEMORY_SCOPE_AGENT); }
; #define XB_SPIN(cond, bar) do { unsigned _sp = 0; while (cond) { __builtin_amdgcn_s_sleep(1); \
;     if ((++_sp & 255u) == 0u) { if (xb_ld(&(bar)[XB_TMO])) break; if (_sp > XB_SPIN_CAP) { atomicAdd(&(bar)[XB_TMO], 1u); break; } } } } while (0)
; DI void xcd_barrier(const XcdBarrier& b) {
;     ...
;         } else {
;             XB_SPIN(xb_ld(&bar[XB_XGEN(b.x)]) == gen, bar);
;             __builtin_amdgcn_fence(__ATOMIC_ACQUIRE, "agent");
;             asm volatile("s_waitcnt vmcnt(0)" ::: "memory");
;         }
;     }
;     __syncthreads();
.Lxb6_done:
.LBB0_970:
	s_or_b64 exec, exec, s[4:5]
	s_waitcnt lgkmcnt(0)
	s_barrier

; DI unsigned xb_ld(unsigned* p)              { return __hip_atomic_load(p, __ATOMIC_RELAXED, __HIP_MEMORY_SCOPE_AGENT); }
; #define XB_SPIN(cond, bar) do { unsigned _sp = 0; while (cond) { __builtin_amdgcn_s_sleep(1); \
;     if ((++_sp & 255u) == 0u) { if (xb_ld(&(bar)[XB_TMO])) break; if (_sp > XB_SPIN_CAP) { atomicAdd(&(bar)[XB_TMO], 1u); break; } } } } while (0)
; DI void xcd_barrier(const XcdBarrier& b) {
;     ...
;         } else {
;             XB_SPIN(xb_ld(&bar[XB_XGEN(b.x)]) == gen, bar);
;             __builtin_amdgcn_fence(__ATOMIC_ACQUIRE, "agent");
;             asm volatile("s_waitcnt vmcnt(0)" ::: "memory");
;         }
;     }
;     __syncthreads();
.Lxb10_done:
.LBB0_1289:
	s_or_b64 exec, exec, s[2:3]
	s_waitcnt lgkmcnt(0)
	s_barrier
